# same as K+V DMA version but V ks3 fragments read in PV2 gaps into freed V2x registers (no LDS reads in QK segment)
# baseline (speedup 1.0000x reference)
; template <int MODE, bool FROZEN = false>
; __device__ __forceinline__ bool attn_unit(LAS unsigned char* lds, const Params& p, int l, int ua, int ub) {
;     ...
;         const float* lq = p.diff_lambda + (size_t)l * 256;
;         const float s1 = wave_sum(lq[lane] * lq[64 + lane]), s2 = wave_sum(lq[128 + lane] * lq[192 + lane]);
;         lam_init = 0.8f - 0.6f * expf(-0.3f * (float)l);
;         lam = expf(s1) - expf(s2) + lam_init;
;     } else {
;         const int g = ua, qb = ub, hq = g * 4 + (wid >> 1); qtok0 = qb * 64 + (wid & 1) * 32; lut_sel = wid >> 1;
;         qcol = 3072 + hq * 64; kcol = 3584 + g * 64; vcol = 1024 + g * 64; ocol = hq * 64;
;         const int tlo = max(qb - 2, 0), thi = min(qb + 2, S / 64 - 1); kt0 = tlo * 64; NT = thi - tlo + 1; wt_hi = NT;
;         for (int i = tid; i < 4 * 449; i += 512) { const int hh = i / 449, rel = i % 449 - 224; lut[i] = (rel >= -128 && rel <= 128) ? p.rel_bias[t5_bucket(rel) * 12 + 4 + g * 4 + hh] * LOG2E : NEGBIG; }
;         m_run = p.gqa_sink[l * 8 + hq] * LOG2E; l_run = (hi == 0) ? 1.0f : 0.0f;
;     }
;     bf16x8 qf[4];
;     { const bf16_t* qp = proj + (size_t)(qtok0 + r32) * NPROJ + qcol + 8 * hi;
; #pragma unroll
;       for (int d0 = 0; d0 < 4; ++d0) qf[d0] = *(const bf16x8*)(qp + 16 * d0); }
;     f32x16 o[NB];
; #pragma unroll
;     for (int nb = 0; nb < NB; ++nb)
; #pragma unroll
;         for (int r = 0; r < 16; ++r) o[nb][r] = 0.f;
;     u32x4 kr[NKC], vr[NVC];
;     unsigned ksrc[NKC], vsrc[NVC]; int kdst[NKC], vdst[NVC];
;     const bf16_t* kvbase = proj + (size_t)kt0 * NPROJ;
; #pragma unroll
;     for (int i = 0; i < NKC; ++i) { const int cid = tid + 512 * i, row = cid / KCH, ch = cid % KCH; ksrc[i] = (unsigned)(row * NPROJ + kcol + ch * 8); kdst[i] = OFF_K + row * KPB + ch * 16; }
; #pragma unroll
;     for (int i = 0; i < NVC; ++i) { const int cid = tid + 512 * i, row = cid >> 3, ch = cid & 7; vsrc[i] = (unsigned)((vcol + row) * S + ch * 8); vdst[i] = OFF_V + row * VTP + (ch >> 1) * 32 + (ch & 1) * 8; }
;     const bf16_t* vtbase = vtg + kt0;
.LBB0_116:
	v_mul_f32_e32 v55, 0x3fb8aa3b, v53
	s_mov_b32 s8, 0x3fb8aa3b
	v_fma_f32 v56, v53, s8, -v55
	v_fmac_f32_e32 v56, 0x32a5705f, v53
	v_rndne_f32_e32 v53, v55
	v_sub_f32_e32 v55, v55, v53
	v_add_f32_e32 v55, v55, v56
	v_mul_f32_e32 v56, 0x3fb8aa3b, v54
	v_fma_f32 v57, v54, s8, -v56
	v_fmac_f32_e32 v57, 0x32a5705f, v54
	v_rndne_f32_e32 v54, v56
	v_exp_f32_e32 v55, v55
	v_cvt_i32_f32_e32 v53, v53
	v_sub_f32_e32 v56, v56, v54
	v_add_f32_e32 v56, v56, v57
	v_exp_f32_e32 v56, v56
	v_cvt_i32_f32_e32 v54, v54
	v_ldexp_f32 v53, v55, v53
	v_cndmask_b32_e64 v53, 0, v53, s[40:41]
	v_mov_b32_e32 v55, 0x7f800000
	v_cndmask_b32_e64 v167, v55, v53, s[42:43]
	v_ldexp_f32 v53, v56, v54
	v_cndmask_b32_e64 v53, 0, v53, s[0:1]
	s_lshl_b32 s0, s51, 7
	s_and_b32 s0, s0, 0x2000
	s_lshl_b32 s1, s57, 7
	v_cndmask_b32_e64 v168, v55, v53, s[4:5]
	s_add_i32 s4, s0, s1
	s_or_b32 s4, s4, s58
	v_mul_u32_u24_e32 v53, 0x90, v52
	v_add_lshl_u32 v52, s4, v52, 2
	v_sub_u32_e32 v52, v32, v52
	s_or_b32 s1, s58, s1
	v_add3_u32 v101, 0, v53, v32
	v_add_u32_e32 v102, 0, v52
	s_add_i32 s1, s1, s0
	v_mov_b64_e32 v[98:99], v[50:51]
	v_mov_b64_e32 v[82:83], v[50:51]
	v_mov_b64_e32 v[66:67], v[50:51]
	s_add_i32 s8, s4, 0xffffff81
	s_sub_i32 s12, 33, s1
	s_mov_b32 s13, 0
	v_mov_b64_e32 v[96:97], v[48:49]
	v_mov_b64_e32 v[94:95], v[46:47]
	v_mov_b64_e32 v[92:93], v[44:45]
	v_mov_b64_e32 v[90:91], v[42:43]
	v_mov_b64_e32 v[88:89], v[40:41]
	v_mov_b64_e32 v[86:87], v[38:39]
	v_mov_b64_e32 v[84:85], v[36:37]
	v_mov_b64_e32 v[80:81], v[48:49]
	v_mov_b64_e32 v[78:79], v[46:47]
	v_mov_b64_e32 v[76:77], v[44:45]
	v_mov_b64_e32 v[74:75], v[42:43]
	v_mov_b64_e32 v[72:73], v[40:41]
	v_mov_b64_e32 v[70:71], v[38:39]
	v_mov_b64_e32 v[68:69], v[36:37]
	v_mov_b64_e32 v[64:65], v[48:49]
	v_mov_b64_e32 v[62:63], v[46:47]
	v_mov_b64_e32 v[60:61], v[44:45]
	v_mov_b64_e32 v[58:59], v[42:43]
	v_mov_b64_e32 v[56:57], v[40:41]
	v_mov_b64_e32 v[54:55], v[38:39]
	v_mov_b64_e32 v[52:53], v[36:37]
	v_mov_b64_e32 v[206:207], 0
	v_mov_b64_e32 v[208:209], 0
	v_mov_b64_e32 v[210:211], 0
	v_mov_b64_e32 v[212:213], 0
	v_mov_b64_e32 v[214:215], 0
	v_mov_b64_e32 v[216:217], 0
	v_mov_b64_e32 v[236:237], 0
	v_mov_b64_e32 v[238:239], 0
	v_mov_b64_e32 v[244:245], 0
	v_mov_b64_e32 v[246:247], 0
	s_waitcnt vmcnt(0)
	v_readfirstlane_b32 s98, v228
	s_lshr_b32 s98, s98, 6
	s_lshl_b32 s98, s98, 11
	v_lshrrev_b32_e32 v140, 4, v228
	v_mul_u32_u24_e32 v140, 0xf00, v140
	v_and_b32_e32 v141, 15, v228
	v_lshl_add_u32 v140, v141, 3, v140
	v_sub_u32_e32 v140, v196, v140
	s_nop 0
	v_readfirstlane_b32 s99, v140
	s_lshl_b32 s99, s99, 1
	s_add_i32 s99, s99, 0xf0000
	v_and_b32_e32 v140, 63, v228
	v_lshrrev_b32_e32 v141, 6, v228
	v_lshl_add_u32 v140, v141, 7, v140
	v_add_u32_e32 v141, 64, v140
	v_and_b32_e32 v142, 63, v228
	v_add_u32_e32 v142, 0x400, v142
	v_mul_u32_u24_e32 v132, 0xf10, v140
	v_mul_u32_u24_e32 v133, 0xf10, v141
	v_mul_u32_u24_e32 v134, 0xf10, v142
	v_lshrrev_b32_e32 v132, 16, v132
	v_lshrrev_b32_e32 v133, 16, v133
	v_lshrrev_b32_e32 v134, 16, v134
	v_mul_u32_u24_e32 v135, 17, v132
	v_sub_u32_e32 v140, v140, v135
	v_mul_u32_u24_e32 v135, 17, v133
	v_sub_u32_e32 v141, v141, v135
	v_mul_u32_u24_e32 v135, 17, v134
	v_sub_u32_e32 v142, v142, v135
	v_cmp_eq_u32_e32 vcc, 16, v140
	s_nop 1
	v_cndmask_b32_e64 v140, v140, 0, vcc
	v_cmp_eq_u32_e32 vcc, 16, v141
	s_nop 1
	v_cndmask_b32_e64 v141, v141, 0, vcc
	v_cmp_eq_u32_e32 vcc, 16, v142
	s_nop 1
	v_cndmask_b32_e64 v142, v142, 0, vcc
	v_mul_u32_u24_e32 v132, 0x1e00, v132
	v_mul_u32_u24_e32 v133, 0x1e00, v133
	v_mul_u32_u24_e32 v134, 0x1e00, v134
	v_lshl_add_u32 v132, v140, 4, v132
	v_lshl_add_u32 v133, v141, 4, v133
	v_lshl_add_u32 v134, v142, 4, v134
	v_lshrrev_b32_e32 v140, 3, v228
	v_lshlrev_b32_e32 v140, 14, v140
	v_and_b32_e32 v141, 7, v228
	v_lshl_add_u32 v140, v141, 3, v140
	v_sub_u32_e32 v140, v154, v140
	s_nop 0
	v_readfirstlane_b32 s101, v140
	s_lshl_b32 s101, s101, 1
	v_and_b32_e32 v140, 63, v228
	v_lshrrev_b32_e32 v141, 6, v228
	v_lshl_add_u32 v142, v141, 6, v140
	v_add_u32_e32 v142, 0x400, v142
	v_lshl_add_u32 v140, v141, 7, v140
	v_add_u32_e32 v141, 64, v140
	v_mul_u32_u24_e32 v135, 0x1c72, v140
	v_mul_u32_u24_e32 v136, 0x1c72, v141
	v_mul_u32_u24_e32 v137, 0x1c72, v142
	v_lshrrev_b32_e32 v135, 16, v135
	v_lshrrev_b32_e32 v136, 16, v136
	v_lshrrev_b32_e32 v137, 16, v137
	v_mul_u32_u24_e32 v143, 9, v135
	v_sub_u32_e32 v140, v140, v143
	v_mul_u32_u24_e32 v143, 9, v136
	v_sub_u32_e32 v141, v141, v143
	v_mul_u32_u24_e32 v143, 9, v137
	v_sub_u32_e32 v142, v142, v143
	v_cmp_eq_u32_e32 vcc, 8, v140
	s_nop 1
	v_cndmask_b32_e64 v140, v140, 0, vcc
	v_cmp_eq_u32_e32 vcc, 8, v141
	s_nop 1
	v_cndmask_b32_e64 v141, v141, 0, vcc
	v_cmp_eq_u32_e32 vcc, 8, v142
	s_nop 1
	v_cndmask_b32_e64 v142, v142, 0, vcc
	v_lshlrev_b32_e32 v135, 15, v135
	v_lshlrev_b32_e32 v136, 15, v136
	v_lshlrev_b32_e32 v137, 15, v137
	v_lshl_add_u32 v135, v140, 4, v135
	v_lshl_add_u32 v136, v141, 4, v136
	v_lshl_add_u32 v137, v142, 4, v137
	v_readfirstlane_b32 s100, v228
	s_lshr_b32 s100, s100, 8
	s_cmp_eq_u32 s100, 0
	s_cbranch_scc1 .Lattn_prio_skip
	s_setprio 1

; #define LAS __attribute__((address_space(3)))
; #define VLOAD(ks, DST) do { const LAS unsigned char* vp_ = Vb + (ks) * 32; \
;         _Pragma("unroll") for (int nb = 0; nb < NB; ++nb) DST[nb] = *(const LAS bf16x8*)(vp_ + nb * 32 * VTP); } while (0)
; #define PVMMA(SRC, PF) do { _Pragma("unroll") for (int nb = 0; nb < NB; ++nb) o[nb] = __builtin_amdgcn_mfma_f32_32x32x16_bf16(SRC[nb], PF, o[nb], 0, 0, 0); } while (0)
; #define SBAR_() __builtin_amdgcn_sched_barrier(0)
; template <int MODE, bool FROZEN = false>
; __device__ __forceinline__ bool attn_unit(LAS unsigned char* lds, const Params& p, int l, int ua, int ub) {
;     ...
;         {
;             const size_t advk = (size_t)min(t + 3, NT - 1) * 64 * NPROJ, advv = (size_t)min(t + 2, NT - 1) * 64;
; #pragma unroll
;             for (int i = 0; i < NKC; ++i) kr[i] = *(const u32x4*)(kvbase + advk + ksrc[i]);
; #pragma unroll
;             for (int i = 0; i < NVC; ++i) vr[i] = *(const u32x4*)(vtbase + advv + vsrc[i]);
;         }
;         f32x16 sA0 = sB0, sA1 = sB1;
;         const float c2 = cbB - m_run;
;         const LAS unsigned char* Vb = lds + OFF_V + (t & 1) * VBUF + vlane_off;
;         const LAS unsigned char* Kb = lds + OFF_K + ((t + 1) & 1) * KBUF + klane_off;
;     ...
;         bf16x8 kf0[4], kf1[4], va[NB], vb[NB], pf0, pf1; float ps0, ps1, ps2, ps3;
;         VLOAD(0, va);
;         EXPCVT(0, pf0, ps0);
;         SBAR_();
;         VLOAD(1, vb); PVMMA(va, pf0); EXPCVT(1, pf1, ps1); _Pragma("unroll") for (int g_ = 0; g_ < NB; ++g_) { __builtin_amdgcn_sched_group_barrier(0x008, 1, 0); __builtin_amdgcn_sched_group_barrier(0x100, 1, 0); __builtin_amdgcn_sched_group_barrier(0x400, 8 / NB, 0); __builtin_amdgcn_sched_group_barrier(0x002, 12 / NB, 0); } SBAR_();
.LBB0_117:
.LBB0_118:
	s_add_i32 s14, s4, 1
	s_bitcmp1_b32 s14, 0
	s_cselect_b32 s15, 0x4400, 0
	s_cselect_b32 s100, 0, 0x4800
	v_add_u32_e32 v194, s100, v101
	s_sub_i32 s5, 0x4400, s15
	s_min_i32 s10, s4, 0xfd
	s_mul_i32 s10, s10, 0x78000
	s_add_u32 s10, s34, s10
	s_addc_u32 s11, s35, 0
	s_add_u32 s10, s10, s99
	s_addc_u32 s11, s11, 0
	s_lshl_b32 s0, s14, 7
	s_add_u32 s0, s6, s0
	s_addc_u32 s1, s7, 0
	s_add_u32 s0, s0, s101
	s_addc_u32 s1, s1, 0
	ds_read_b128 v[112:115], v194 offset:34816
	ds_read_b128 v[170:173], v194 offset:39424
	ds_read_b128 v[174:177], v194 offset:44032
	ds_read_b128 v[178:181], v194 offset:48640
	v_exp_f32_e32 v103, v16
	v_exp_f32_e32 v104, v17
	v_mfma_f32_32x32x16_bf16 v[52:67], v[236:239], v[244:247], v[52:67]
	v_exp_f32_e32 v105, v18
	v_exp_f32_e32 v106, v19
	v_cvt_pk_bf16_f32 v16, v103, v104
	v_mfma_f32_32x32x16_bf16 v[36:51], v[206:209], v[244:247], v[36:51]
	s_add_i32 m0, s5, s98
	s_nop 0
	global_load_lds_dwordx4 v132, s[10:11]
	v_exp_f32_e32 v107, v20
	v_exp_f32_e32 v108, v21
	v_cvt_pk_bf16_f32 v17, v105, v106
	v_mfma_f32_32x32x16_bf16 v[84:99], v[210:213], v[244:247], v[84:99]
	s_add_i32 m0, m0, 0x400
	s_nop 0
	global_load_lds_dwordx4 v133, s[10:11]
	v_exp_f32_e32 v109, v22
	v_exp_f32_e32 v110, v23
	v_cvt_pk_bf16_f32 v18, v107, v108
	v_mfma_f32_32x32x16_bf16 v[68:83], v[214:217], v[244:247], v[68:83]
	s_cmp_lg_u32 s98, 0
	s_cbranch_scc1 .Lkdma_skip
	s_add_i32 m0, s5, 0x4000
	s_nop 0
	global_load_lds_dwordx4 v134, s[10:11]

; #define LAS __attribute__((address_space(3)))
; #define ATT_MAX3(dst) do { float tm_ = max3f(sB0[0], sB1[0], sB0[1]), tn_ = max3f(sB1[1], sB0[2], sB1[2]); \
;         _Pragma("unroll") for (int r = 3; r < 15; r += 2) { tm_ = max3f(tm_, sB0[r], sB1[r]); tn_ = max3f(tn_, sB0[r + 1], sB1[r + 1]); } \
;         tm_ = max3f(tm_, sB0[15], sB1[15]); dst = max3f(tm_, tn_, tn_); } while (0)
; #define SBAR_() __builtin_amdgcn_sched_barrier(0)
; template <int MODE, bool FROZEN = false>
; __device__ __forceinline__ bool attn_unit(LAS unsigned char* lds, const Params& p, int l, int ua, int ub) {
;     ...
;         VLOAD(0, va);
;         EXPCVT(0, pf0, ps0);
;         SBAR_();
;         VLOAD(1, vb); PVMMA(va, pf0); EXPCVT(1, pf1, ps1); _Pragma("unroll") for (int g_ = 0; g_ < NB; ++g_) { __builtin_amdgcn_sched_group_barrier(0x008, 1, 0); __builtin_amdgcn_sched_group_barrier(0x100, 1, 0); __builtin_amdgcn_sched_group_barrier(0x400, 8 / NB, 0); __builtin_amdgcn_sched_group_barrier(0x002, 12 / NB, 0); } SBAR_();
;         VLOAD(2, va);
; #pragma unroll
;         for (int d0 = 0; d0 < 4; ++d0) { kf0[d0] = *(const LAS bf16x8*)(Kb + d0 * 32); kf1[d0] = *(const LAS bf16x8*)(Kb + 32 * KPB + d0 * 32); }
;         PVMMA(vb, pf1); EXPCVT(2, pf0, ps2); _Pragma("unroll") for (int g_ = 0; g_ < NB; ++g_) { __builtin_amdgcn_sched_group_barrier(0x008, 1, 0); __builtin_amdgcn_sched_group_barrier(0x100, 1, 0); __builtin_amdgcn_sched_group_barrier(0x400, 8 / NB, 0); __builtin_amdgcn_sched_group_barrier(0x002, 12 / NB, 0); } SBAR_();
;         {
;             f32x16 z0, z1;
; #pragma unroll
;             for (int r = 0; r < 16; ++r) { z0[r] = 0.f; z1[r] = 0.f; }
; #pragma unroll
;             for (int d0 = 0; d0 < 4; ++d0) { z0 = __builtin_amdgcn_mfma_f32_32x32x16_bf16(kf0[d0], qf[d0], z0, 0, 0, 0); z1 = __builtin_amdgcn_mfma_f32_32x32x16_bf16(kf1[d0], qf[d0], z1, 0, 0, 0); }
;             sB0 = z0; sB1 = z1;
;         }
;         EXPCVT(3, pf1, ps3);
; #pragma unroll
;         for (int g_ = 0; g_ < 8; ++g_) { __builtin_amdgcn_sched_group_barrier(0x008, 1, 0); __builtin_amdgcn_sched_group_barrier(0x400, 1, 0); __builtin_amdgcn_sched_group_barrier(0x002, 2, 0); }
;         SBAR_();
;         float tmr;
;         VLOAD(3, vb); SBAR_();
;         PVMMA(va, pf0); if constexpr (!FROZEN) ATT_MAX3(tmr); else tmr = 0.f; PVMMA(vb, pf1);
;         const float ps = (ps0 + ps1) + (ps2 + ps3);
.Lvdma_skip:
	v_exp_f32_e32 v115, v28
	v_exp_f32_e32 v170, v29
	s_nop 0
	v_cvt_pk_bf16_f32 v26, v115, v170
	s_waitcnt lgkmcnt(6)
	v_mfma_f32_32x32x16_bf16 v[52:67], v[178:181], v[16:19], v[52:67]
	ds_read_b128 v[16:19], v194 offset:48672
	v_exp_f32_e32 v171, v30
	v_exp_f32_e32 v172, v31
	s_nop 0
	v_cvt_pk_bf16_f32 v27, v171, v172
	s_waitcnt lgkmcnt(6)
	s_nop 0
	v_mfma_f32_32x32x16_bf16 v[36:51], v[20:23], v[24:27], v[36:51]
	ds_read_b128 v[190:193], v194 offset:34880
	ds_read_b128 v[20:23], v195 offset:8736
	v_exp_f32_e32 v173, v0
	v_exp_f32_e32 v174, v1
	s_nop 0
	v_cvt_pk_bf16_f32 v202, v173, v174
	s_waitcnt lgkmcnt(6)
	v_mfma_f32_32x32x16_bf16 v[84:99], v[182:185], v[24:27], v[84:99]
	ds_read_b128 v[206:209], v194 offset:39488
	v_exp_f32_e32 v175, v2
	v_exp_f32_e32 v176, v3
	s_nop 0
	v_cvt_pk_bf16_f32 v203, v175, v176
	s_waitcnt lgkmcnt(5)
	v_mfma_f32_32x32x16_bf16 v[68:83], v[186:189], v[24:27], v[68:83]
	ds_read_b128 v[210:213], v194 offset:44096
	v_exp_f32_e32 v177, v4
	v_exp_f32_e32 v178, v5
	s_nop 0
	v_cvt_pk_bf16_f32 v204, v177, v178
	s_waitcnt lgkmcnt(4)
	v_mfma_f32_32x32x16_bf16 v[52:67], v[16:19], v[24:27], v[52:67]
	ds_read_b128 v[214:217], v194 offset:48704
	ds_read_b128 v[236:239], v194 offset:48736
	ds_read_b128 v[0:3], v195 offset:8704
	v_exp_f32_e32 v179, v6
	v_exp_f32_e32 v180, v7
	s_nop 0
	v_cvt_pk_bf16_f32 v205, v179, v180
	v_exp_f32_e32 v181, v8
	v_exp_f32_e32 v182, v9
	s_waitcnt lgkmcnt(6)
	v_mfma_f32_32x32x16_bf16 v[36:51], v[190:193], v[202:205], v[36:51]
	ds_read_b128 v[24:27], v195 offset:8768
	v_exp_f32_e32 v183, v10
	v_exp_f32_e32 v184, v11
	v_cvt_pk_bf16_f32 v244, v181, v182
	s_waitcnt lgkmcnt(5)
	v_mfma_f32_32x32x16_bf16 v[84:99], v[206:209], v[202:205], v[84:99]
	ds_read_b128 v[28:31], v195 offset:8800
	ds_read_b128 v[206:209], v194 offset:34912
	v_exp_f32_e32 v185, v12
	v_exp_f32_e32 v186, v13
	v_cvt_pk_bf16_f32 v245, v183, v184
	s_waitcnt lgkmcnt(6)
	v_mfma_f32_32x32x16_bf16 v[68:83], v[210:213], v[202:205], v[68:83]
	ds_read_b128 v[16:19], v195
	ds_read_b128 v[210:213], v194 offset:39520
	v_exp_f32_e32 v187, v14
	v_exp_f32_e32 v188, v15
	v_cvt_pk_bf16_f32 v246, v185, v186
	s_waitcnt lgkmcnt(7)
	v_mfma_f32_32x32x16_bf16 v[52:67], v[214:217], v[202:205], v[52:67]
	ds_read_b128 v[214:217], v194 offset:44128
	v_cvt_pk_bf16_f32 v247, v187, v188
	s_waitcnt lgkmcnt(6)
	v_mfma_f32_32x32x16_bf16 v[0:15], v[0:3], v[116:119], 0
	v_add_f32_e32 v105, v105, v106
	v_add_f32_e32 v106, v107, v108
	v_add_f32_e32 v107, v109, v110
	v_add_f32_e32 v103, v103, v104
	v_mfma_f32_32x32x16_bf16 v[0:15], v[20:23], v[120:123], v[0:15]
	v_add_f32_e32 v106, v106, v107
	v_add_f32_e32 v103, v103, v105
	v_add_f32_e32 v105, v115, v170
	v_add_f32_e32 v107, v171, v172
	s_waitcnt lgkmcnt(5)
	v_mfma_f32_32x32x16_bf16 v[0:15], v[24:27], v[124:127], v[0:15]
	v_add_f32_e32 v104, v113, v114
	v_add_f32_e32 v105, v105, v107
	v_add_f32_e32 v107, v111, v112
	v_add_f32_e32 v104, v107, v104
	s_waitcnt lgkmcnt(4)
	v_mfma_f32_32x32x16_bf16 v[0:15], v[28:31], v[128:131], v[0:15]
	v_add_f32_e32 v107, v177, v178
	v_add_f32_e32 v108, v179, v180
	v_add_f32_e32 v104, v104, v105
	v_add_f32_e32 v105, v175, v176
	s_waitcnt lgkmcnt(2)
	v_mfma_f32_32x32x16_bf16 v[16:31], v[16:19], v[116:119], 0
	v_add_f32_e32 v107, v107, v108
	v_add_f32_e32 v108, v173, v174
	v_add_f32_e32 v105, v108, v105
	v_add_f32_e32 v105, v105, v107
	s_cmpk_gt_i32 s12, 0x7f
	s_cselect_b64 s[0:1], -1, 0
	s_cmpk_gt_i32 s8, 0x7f
	s_cselect_b64 s[4:5], -1, 0
	s_or_b64 s[10:11], s[0:1], s[4:5]
	v_mfma_f32_32x32x16_bf16 v[16:31], v[218:221], v[120:123], v[16:31]
	v_add_f32_e32 v107, v185, v186
	v_add_f32_e32 v108, v187, v188
	v_add_f32_e32 v103, v103, v106
	v_add_f32_e32 v106, v183, v184
	s_and_b64 vcc, exec, s[10:11]
	v_mfma_f32_32x32x16_bf16 v[16:31], v[222:225], v[124:127], v[16:31]
	v_add_f32_e32 v107, v107, v108
	v_add_f32_e32 v108, v181, v182
	v_add_f32_e32 v106, v108, v106
	v_add_f32_e32 v106, v106, v107
	v_mfma_f32_32x32x16_bf16 v[16:31], v[248:251], v[128:131], v[16:31]
	v_add_f32_e32 v103, v103, v104
	v_add_f32_e32 v104, v105, v106
	v_add_f32_e32 v103, v103, v104
	v_add_f32_e32 v100, v100, v103
	s_cbranch_vccnz .LBB0_120
	v_add_u32_e32 v189, s13, v102
	v_add_u32_e32 v190, 0x11c80, v189
	v_add_u32_e32 v192, 0x11c88, v189
	v_add_u32_e32 v194, 0x11ca0, v189
	v_add_u32_e32 v138, 0x11ca8, v189
	ds_read2_b32 v[190:191], v190 offset1:1
	ds_read2_b32 v[192:193], v192 offset1:1
	ds_read2_b32 v[194:195], v194 offset1:1
	ds_read2_b32 v[138:139], v138 offset1:1
	v_add_u32_e32 v140, 0x11cc0, v189
	v_add_u32_e32 v142, 0x11cc8, v189
	v_add_u32_e32 v144, 0x11ce0, v189
	v_add_u32_e32 v146, 0x11ce8, v189
	ds_read2_b32 v[140:141], v140 offset1:1
	ds_read2_b32 v[142:143], v142 offset1:1
	ds_read2_b32 v[144:145], v144 offset1:1
	ds_read2_b32 v[146:147], v146 offset1:1
	s_waitcnt lgkmcnt(7)
	v_sub_f32_e32 v191, v191, v169
	v_sub_f32_e32 v190, v190, v169
	s_waitcnt lgkmcnt(2)
	v_sub_f32_e32 v143, v143, v169
	v_sub_f32_e32 v141, v141, v169
	v_sub_f32_e32 v140, v140, v169
	v_sub_f32_e32 v142, v142, v169
	s_waitcnt lgkmcnt(1)
	v_sub_f32_e32 v145, v145, v169
	v_sub_f32_e32 v144, v144, v169
	s_waitcnt lgkmcnt(0)
	v_sub_f32_e32 v147, v147, v169
	v_sub_f32_e32 v146, v146, v169
	v_sub_f32_e32 v193, v193, v169
	v_sub_f32_e32 v192, v192, v169
	v_sub_f32_e32 v195, v195, v169
	v_sub_f32_e32 v194, v194, v169
	v_sub_f32_e32 v139, v139, v169
	v_sub_f32_e32 v138, v138, v169
	v_pk_add_f32 v[22:23], v[22:23], v[138:139]
	v_pk_add_f32 v[20:21], v[20:21], v[194:195]
	v_pk_add_f32 v[18:19], v[18:19], v[192:193]
	v_pk_add_f32 v[16:17], v[16:17], v[190:191]
	v_pk_add_f32 v[30:31], v[30:31], v[146:147]
	v_pk_add_f32 v[28:29], v[28:29], v[144:145]
	v_pk_add_f32 v[26:27], v[26:27], v[142:143]
	v_pk_add_f32 v[24:25], v[24:25], v[140:141]
	v_add_u32_e32 v190, 0x11d00, v189
	v_add_u32_e32 v192, 0x11d08, v189
	v_add_u32_e32 v194, 0x11d20, v189
	v_add_u32_e32 v138, 0x11d28, v189
	ds_read2_b32 v[190:191], v190 offset1:1
	ds_read2_b32 v[192:193], v192 offset1:1
	ds_read2_b32 v[194:195], v194 offset1:1
	ds_read2_b32 v[138:139], v138 offset1:1
	v_add_u32_e32 v140, 0x11d40, v189
	v_add_u32_e32 v142, 0x11d48, v189
	v_add_u32_e32 v144, 0x11d60, v189
	ds_read2_b32 v[140:141], v140 offset1:1
	v_add_u32_e32 v189, 0x11d68, v189
	ds_read2_b32 v[142:143], v142 offset1:1
	ds_read2_b32 v[144:145], v144 offset1:1
	ds_read2_b32 v[146:147], v189 offset1:1
	s_waitcnt lgkmcnt(7)
	v_sub_f32_e32 v191, v191, v169
	v_sub_f32_e32 v190, v190, v169
	s_waitcnt lgkmcnt(3)
	v_sub_f32_e32 v141, v141, v169
	v_sub_f32_e32 v140, v140, v169
	s_waitcnt lgkmcnt(2)
	v_sub_f32_e32 v143, v143, v169
	v_sub_f32_e32 v142, v142, v169
	s_waitcnt lgkmcnt(1)
	v_sub_f32_e32 v145, v145, v169
	v_sub_f32_e32 v144, v144, v169
	s_waitcnt lgkmcnt(0)
	v_sub_f32_e32 v147, v147, v169
	v_sub_f32_e32 v146, v146, v169
	v_sub_f32_e32 v193, v193, v169
	v_sub_f32_e32 v192, v192, v169
	v_sub_f32_e32 v195, v195, v169
	v_sub_f32_e32 v194, v194, v169
	v_sub_f32_e32 v139, v139, v169
	v_sub_f32_e32 v138, v138, v169
	v_pk_add_f32 v[6:7], v[6:7], v[138:139]
	v_pk_add_f32 v[4:5], v[4:5], v[194:195]
	v_pk_add_f32 v[2:3], v[2:3], v[192:193]
	v_pk_add_f32 v[0:1], v[0:1], v[190:191]
	v_pk_add_f32 v[14:15], v[14:15], v[146:147]
	v_pk_add_f32 v[12:13], v[12:13], v[144:145]
	v_pk_add_f32 v[10:11], v[10:11], v[142:143]
	v_pk_add_f32 v[8:9], v[8:9], v[140:141]
.LBB0_120:
	s_andn2_b64 vcc, exec, s[10:11]
	s_cbranch_vccnz .LBB0_123
	v_cndmask_b32_e64 v103, 0, v161, s[4:5]
	v_cndmask_b32_e64 v103, v103, v159, s[0:1]
	v_cmp_neq_f32_e32 vcc, v103, v169
	s_cbranch_vccz .LBB0_123
	v_sub_f32_e32 v104, v169, v103
	v_exp_f32_e32 v104, v104
	v_mov_b32_e32 v169, v103
	s_waitcnt lgkmcnt(0)
	v_mfma_f32_32x32x16_bf16 v[52:67], v[236:239], v[244:247], v[52:67]
	v_mfma_f32_32x32x16_bf16 v[36:51], v[206:209], v[244:247], v[36:51]
	v_mfma_f32_32x32x16_bf16 v[84:99], v[210:213], v[244:247], v[84:99]
	v_mfma_f32_32x32x16_bf16 v[68:83], v[214:217], v[244:247], v[68:83]
	v_mov_b32_e32 v244, 0
	v_mov_b32_e32 v245, 0
	v_mov_b32_e32 v246, 0
	v_mov_b32_e32 v247, 0
	s_nop 7
	s_nop 7
	v_pk_mul_f32 v[50:51], v[104:105], v[50:51] op_sel_hi:[0,1]
	v_pk_mul_f32 v[48:49], v[104:105], v[48:49] op_sel_hi:[0,1]
	v_pk_mul_f32 v[46:47], v[104:105], v[46:47] op_sel_hi:[0,1]
	v_pk_mul_f32 v[44:45], v[104:105], v[44:45] op_sel_hi:[0,1]
	v_pk_mul_f32 v[42:43], v[104:105], v[42:43] op_sel_hi:[0,1]
	v_pk_mul_f32 v[40:41], v[104:105], v[40:41] op_sel_hi:[0,1]
	v_pk_mul_f32 v[38:39], v[104:105], v[38:39] op_sel_hi:[0,1]
	v_pk_mul_f32 v[36:37], v[104:105], v[36:37] op_sel_hi:[0,1]
	v_pk_mul_f32 v[98:99], v[104:105], v[98:99] op_sel_hi:[0,1]
	v_pk_mul_f32 v[96:97], v[104:105], v[96:97] op_sel_hi:[0,1]
	v_pk_mul_f32 v[94:95], v[104:105], v[94:95] op_sel_hi:[0,1]
	v_pk_mul_f32 v[92:93], v[104:105], v[92:93] op_sel_hi:[0,1]
	v_pk_mul_f32 v[90:91], v[104:105], v[90:91] op_sel_hi:[0,1]
	v_pk_mul_f32 v[88:89], v[104:105], v[88:89] op_sel_hi:[0,1]
	v_pk_mul_f32 v[86:87], v[104:105], v[86:87] op_sel_hi:[0,1]
	v_pk_mul_f32 v[84:85], v[104:105], v[84:85] op_sel_hi:[0,1]
	v_pk_mul_f32 v[82:83], v[104:105], v[82:83] op_sel_hi:[0,1]
	v_pk_mul_f32 v[80:81], v[104:105], v[80:81] op_sel_hi:[0,1]
	v_pk_mul_f32 v[78:79], v[104:105], v[78:79] op_sel_hi:[0,1]
	v_pk_mul_f32 v[76:77], v[104:105], v[76:77] op_sel_hi:[0,1]
	v_pk_mul_f32 v[74:75], v[104:105], v[74:75] op_sel_hi:[0,1]
	v_pk_mul_f32 v[72:73], v[104:105], v[72:73] op_sel_hi:[0,1]
	v_pk_mul_f32 v[70:71], v[104:105], v[70:71] op_sel_hi:[0,1]
	v_pk_mul_f32 v[68:69], v[104:105], v[68:69] op_sel_hi:[0,1]
	v_pk_mul_f32 v[66:67], v[104:105], v[66:67] op_sel_hi:[0,1]
	v_pk_mul_f32 v[64:65], v[104:105], v[64:65] op_sel_hi:[0,1]
	v_pk_mul_f32 v[62:63], v[104:105], v[62:63] op_sel_hi:[0,1]
	v_pk_mul_f32 v[60:61], v[104:105], v[60:61] op_sel_hi:[0,1]
	v_pk_mul_f32 v[58:59], v[104:105], v[58:59] op_sel_hi:[0,1]
	v_pk_mul_f32 v[56:57], v[104:105], v[56:57] op_sel_hi:[0,1]
	v_pk_mul_f32 v[54:55], v[104:105], v[54:55] op_sel_hi:[0,1]
	v_pk_mul_f32 v[52:53], v[104:105], v[52:53] op_sel_hi:[0,1]
	v_mul_f32_e32 v100, v100, v104

; template <int MODE, bool FROZEN = false>
; __device__ __forceinline__ bool attn_unit(LAS unsigned char* lds, const Params& p, int l, int ua, int ub) {
;     ...
;         f32x16 sA0 = sB0, sA1 = sB1;
;         const float c2 = cbB - m_run;
;         const LAS unsigned char* Vb = lds + OFF_V + (t & 1) * VBUF + vlane_off;
;         const LAS unsigned char* Kb = lds + OFF_K + ((t + 1) & 1) * KBUF + klane_off;
;     ...
;         bf16x8 kf0[4], kf1[4], va[NB], vb[NB], pf0, pf1; float ps0, ps1, ps2, ps3;
;         VLOAD(0, va);
;         EXPCVT(0, pf0, ps0);
;         SBAR_();
;         VLOAD(1, vb); PVMMA(va, pf0); EXPCVT(1, pf1, ps1); _Pragma("unroll") for (int g_ = 0; g_ < NB; ++g_) { __builtin_amdgcn_sched_group_barrier(0x008, 1, 0); __builtin_amdgcn_sched_group_barrier(0x100, 1, 0); __builtin_amdgcn_sched_group_barrier(0x400, 8 / NB, 0); __builtin_amdgcn_sched_group_barrier(0x002, 12 / NB, 0); } SBAR_();
;         VLOAD(2, va);
; #pragma unroll
;         for (int d0 = 0; d0 < 4; ++d0) { kf0[d0] = *(const LAS bf16x8*)(Kb + d0 * 32); kf1[d0] = *(const LAS bf16x8*)(Kb + 32 * KPB + d0 * 32); }
;         PVMMA(vb, pf1); EXPCVT(2, pf0, ps2); _Pragma("unroll") for (int g_ = 0; g_ < NB; ++g_) { __builtin_amdgcn_sched_group_barrier(0x008, 1, 0); __builtin_amdgcn_sched_group_barrier(0x100, 1, 0); __builtin_amdgcn_sched_group_barrier(0x400, 8 / NB, 0); __builtin_amdgcn_sched_group_barrier(0x002, 12 / NB, 0); } SBAR_();
;         {
;             f32x16 z0, z1;
; #pragma unroll
;             for (int r = 0; r < 16; ++r) { z0[r] = 0.f; z1[r] = 0.f; }
; #pragma unroll
;             for (int d0 = 0; d0 < 4; ++d0) { z0 = __builtin_amdgcn_mfma_f32_32x32x16_bf16(kf0[d0], qf[d0], z0, 0, 0, 0); z1 = __builtin_amdgcn_mfma_f32_32x32x16_bf16(kf1[d0], qf[d0], z1, 0, 0, 0); }
;             sB0 = z0; sB1 = z1;
;         }
;         EXPCVT(3, pf1, ps3);
; #pragma unroll
;         for (int g_ = 0; g_ < 8; ++g_) { __builtin_amdgcn_sched_group_barrier(0x008, 1, 0); __builtin_amdgcn_sched_group_barrier(0x400, 1, 0); __builtin_amdgcn_sched_group_barrier(0x002, 2, 0); }
;         SBAR_();
;         float tmr;
;         VLOAD(3, vb); SBAR_();
;         PVMMA(va, pf0); if constexpr (!FROZEN) ATT_MAX3(tmr); else tmr = 0.f; PVMMA(vb, pf1);
;         const float ps = (ps0 + ps1) + (ps2 + ps3);
;     ...
;         l_run += ps;
;         if (t + 1 < NT) { ATT_BIAS(t + 1, tmr); ATT_UPD(tmr); }
.LBB0_125:
	s_setprio 0
	v_mfma_f32_32x32x16_bf16 v[52:67], v[236:239], v[244:247], v[52:67]
	v_mfma_f32_32x32x16_bf16 v[36:51], v[206:209], v[244:247], v[36:51]
	v_mfma_f32_32x32x16_bf16 v[84:99], v[210:213], v[244:247], v[84:99]
	v_mfma_f32_32x32x16_bf16 v[68:83], v[214:217], v[244:247], v[68:83]
	v_add_u32_e32 v33, 0x8800, v101
	ds_read_b128 v[104:107], v33 offset:32256
	ds_read_b128 v[108:111], v101 offset:62464
	ds_read_b128 v[112:115], v101 offset:57856
	ds_read_b128 v[116:119], v101 offset:53248
	v_exp_f32_e32 v125, v16
	v_exp_f32_e32 v127, v17
	v_exp_f32_e32 v129, v18
	v_exp_f32_e32 v131, v19
	v_exp_f32_e32 v103, v20
	v_exp_f32_e32 v21, v21
	v_exp_f32_e32 v17, v22
	v_exp_f32_e32 v19, v23
	v_cvt_pk_bf16_f32 v120, v125, v127
	v_cvt_pk_bf16_f32 v121, v129, v131
	v_cvt_pk_bf16_f32 v122, v103, v21
	v_cvt_pk_bf16_f32 v123, v17, v19
	s_waitcnt lgkmcnt(0)
	s_nop 0
	v_mfma_f32_32x32x16_bf16 v[36:51], v[116:119], v[120:123], v[36:51]
	ds_read_b128 v[116:119], v101 offset:53280
	s_waitcnt vmcnt(3)
	v_exp_f32_e32 v133, v24
	v_exp_f32_e32 v135, v25
	s_nop 0
	v_cvt_pk_bf16_f32 v22, v133, v135
	v_mfma_f32_32x32x16_bf16 v[84:99], v[112:115], v[120:123], v[84:99]
	ds_read_b128 v[112:115], v101 offset:57888
	s_waitcnt vmcnt(1)
	v_exp_f32_e32 v137, v26
	v_exp_f32_e32 v139, v27
	s_nop 0
	v_cvt_pk_bf16_f32 v23, v137, v139
	v_mfma_f32_32x32x16_bf16 v[68:83], v[108:111], v[120:123], v[68:83]
	ds_read_b128 v[108:111], v101 offset:62496
	v_exp_f32_e32 v141, v28
	v_exp_f32_e32 v143, v29
	s_nop 0
	v_cvt_pk_bf16_f32 v24, v141, v143
	v_mfma_f32_32x32x16_bf16 v[52:67], v[104:107], v[120:123], v[52:67]
	ds_read_b128 v[26:29], v33 offset:32288
	v_exp_f32_e32 v121, v30
	v_exp_f32_e32 v31, v31
	s_nop 0
	v_cvt_pk_bf16_f32 v25, v121, v31
	s_waitcnt lgkmcnt(3)
	s_nop 0
	v_mfma_f32_32x32x16_bf16 v[36:51], v[116:119], v[22:25], v[36:51]
	ds_read_b128 v[104:107], v101 offset:53312
	v_exp_f32_e32 v124, v0
	v_exp_f32_e32 v126, v1
	s_nop 0
	v_cvt_pk_bf16_f32 v0, v124, v126
	s_waitcnt lgkmcnt(3)
	v_mfma_f32_32x32x16_bf16 v[84:99], v[112:115], v[22:25], v[84:99]
	ds_read_b128 v[112:115], v101 offset:57920
	v_exp_f32_e32 v128, v2
	v_exp_f32_e32 v130, v3
	s_nop 0
	v_cvt_pk_bf16_f32 v1, v128, v130
	s_waitcnt lgkmcnt(3)
	v_mfma_f32_32x32x16_bf16 v[68:83], v[108:111], v[22:25], v[68:83]
	ds_read_b128 v[108:111], v101 offset:62528
	v_exp_f32_e32 v102, v4
	v_exp_f32_e32 v20, v5
	s_nop 0
	v_cvt_pk_bf16_f32 v2, v102, v20
	s_waitcnt lgkmcnt(3)
	v_mfma_f32_32x32x16_bf16 v[52:67], v[26:29], v[22:25], v[52:67]
	ds_read_b128 v[22:25], v33 offset:32320
	v_exp_f32_e32 v16, v6
	v_exp_f32_e32 v18, v7
	s_nop 0
	v_cvt_pk_bf16_f32 v3, v16, v18
	v_exp_f32_e32 v132, v8
	v_exp_f32_e32 v134, v9
	s_nop 0
	v_cvt_pk_bf16_f32 v4, v132, v134
	v_exp_f32_e32 v136, v10
	v_exp_f32_e32 v138, v11
	s_nop 0
	v_cvt_pk_bf16_f32 v5, v136, v138
	v_exp_f32_e32 v140, v12
	v_exp_f32_e32 v142, v13
	s_nop 0
	v_cvt_pk_bf16_f32 v6, v140, v142
	v_exp_f32_e32 v120, v14
	v_exp_f32_e32 v30, v15
	s_nop 0
	v_cvt_pk_bf16_f32 v7, v120, v30
	ds_read_b128 v[8:11], v101 offset:53344
	ds_read_b128 v[12:15], v101 offset:57952
	ds_read_b128 v[26:29], v101 offset:62560
	ds_read_b128 v[116:119], v33 offset:32352
	s_waitcnt lgkmcnt(7)
	v_mfma_f32_32x32x16_bf16 v[36:51], v[104:107], v[0:3], v[36:51]
	v_add_f32_e64 v16, v16, v18
	v_add_f32_e64 v17, v17, v19
	s_waitcnt lgkmcnt(0)
	s_barrier
	v_cmp_eq_u32_e32 vcc, 0, v148
	s_waitcnt lgkmcnt(0)
	s_barrier
	v_mfma_f32_32x32x16_bf16 v[84:99], v[112:115], v[0:3], v[84:99]
	v_mfma_f32_32x32x16_bf16 v[68:83], v[108:111], v[0:3], v[68:83]
	v_mfma_f32_32x32x16_bf16 v[52:67], v[22:25], v[0:3], v[52:67]
	v_add_f32_e64 v0, v124, v126
	v_add_f32_e64 v1, v125, v127
	v_add_f32_e64 v2, v128, v130
	v_add_f32_e64 v3, v129, v131
	v_add_f32_e64 v0, v0, v2
	v_add_f32_e64 v1, v1, v3
	v_pk_add_f32 v[2:3], v[102:103], v[20:21]
	s_nop 0
	v_pk_add_f32 v[2:3], v[2:3], v[16:17]
	v_mfma_f32_32x32x16_bf16 v[36:51], v[8:11], v[4:7], v[36:51]
	v_add_f32_e64 v0, v0, v2
	v_add_f32_e64 v1, v1, v3
	v_add_f32_e64 v2, v132, v134
	v_add_f32_e64 v3, v133, v135
	v_add_f32_e64 v8, v136, v138
	v_add_f32_e64 v9, v137, v139
	v_pk_add_f32 v[10:11], v[120:121], v[30:31]
	v_pk_add_f32 v[2:3], v[2:3], v[8:9]
	v_pk_add_f32 v[8:9], v[140:141], v[142:143]
	v_mfma_f32_32x32x16_bf16 v[84:99], v[12:15], v[4:7], v[84:99]
	v_add_f32_e64 v8, v8, v10
	v_add_f32_e64 v9, v9, v11
	v_add_f32_e64 v2, v2, v8
	v_add_f32_e64 v3, v3, v9
	v_add_f32_e64 v0, v0, v2
	v_add_f32_e64 v1, v1, v3
	v_add_f32_e32 v0, v0, v1
	v_mfma_f32_32x32x16_bf16 v[68:83], v[26:29], v[4:7], v[68:83]
	v_add_f32_e32 v0, v0, v100
	v_mov_b32_e32 v1, v0
	v_mov_b32_e32 v2, v0
	s_nop 1
	v_permlane32_swap_b32_e32 v1, v2
	v_mfma_f32_32x32x16_bf16 v[52:67], v[116:119], v[4:7], v[52:67]
	s_and_saveexec_b64 s[0:1], vcc
	s_cbranch_execz .LBB0_127
	v_readlane_b32 s4, v254, 47
	s_nop 1
	v_mov_b32_e32 v3, s4
	ds_write_b32 v3, v197
